# EpiSwiglu epilogue regenerated with packed f32 mul/add (same per-element operations), 32-bit store offsets, padded to keep later code addresses
# baseline (speedup 1.0000x reference)
; __device__ __forceinline__ unsigned cvt_pk_bf16(float lo, float hi) { unsigned r; asm volatile("v_cvt_pk_bf16_f32 %0, %1, %2" : "=v"(r) : "v"(lo), "v"(hi)); return r; }
; __device__ __forceinline__ float silu_f(float g) { return g * __builtin_amdgcn_rcpf(1.0f + __expf(-g)); }
;     __device__ __forceinline__ void operator()(const f32x4 (&acc)[2][2][4][2], const Unit& u, int wr, int wc, int fr, int fq, const float (&rsv)[8]) const {
;         const int row0 = u.pm * BM + wr * 64 + fr; const int col0 = u.pn * HALF + wc * 32 + 8 * fq;
; #pragma unroll
;         for (int ai = 0; ai < 2; ++ai)
; #pragma unroll
;             for (int m = 0; m < 4; ++m) { bf16_t* rowp = O + (size_t)(row0 + ai * HALF + m * 16) * ldc + col0;
;                 const float rs = __builtin_amdgcn_rsqf(rsv[ai * 4 + m] * (1.0f / 1024.0f) + 1e-6f);
;                 const f32x4 g0 = acc[ai][0][m][0] * rs, g1 = acc[ai][0][m][1] * rs, u0 = acc[ai][1][m][0] * rs, u1 = acc[ai][1][m][1] * rs; u32x4 w;
;                 w.x = cvt_pk_bf16(silu_f(g0[0]) * u0[0], silu_f(g0[1]) * u0[1]); w.y = cvt_pk_bf16(silu_f(g0[2]) * u0[2], silu_f(g0[3]) * u0[3]);
;                 w.z = cvt_pk_bf16(silu_f(g1[0]) * u1[0], silu_f(g1[1]) * u1[1]); w.w = cvt_pk_bf16(silu_f(g1[2]) * u1[2], silu_f(g1[3]) * u1[3]);
;                 __builtin_nontemporal_store(w, (u32x4*)rowp); }
;     }
.LBB0_1108:
	s_waitcnt vmcnt(8)
	v_fmamk_f32 v172, v170, 0x3a800000, v225
	v_fmamk_f32 v174, v169, 0x3a800000, v225
	v_fmamk_f32 v176, v168, 0x3a800000, v225
	v_fmamk_f32 v178, v167, 0x3a800000, v225
	v_fmamk_f32 v180, v166, 0x3a800000, v225
	v_fmamk_f32 v182, v165, 0x3a800000, v225
	v_fmamk_f32 v184, v164, 0x3a800000, v225
	v_fmamk_f32 v186, v163, 0x3a800000, v225
	v_rsq_f32_e32 v172, v172
	v_rsq_f32_e32 v174, v174
	v_rsq_f32_e32 v176, v176
	v_rsq_f32_e32 v178, v178
	v_rsq_f32_e32 v180, v180
	v_rsq_f32_e32 v182, v182
	v_rsq_f32_e32 v184, v184
	v_rsq_f32_e32 v186, v186
	v_lshl_or_b32 v148, s80, 7, v155
	v_lshlrev_b32_e32 v148, 1, v148
	v_mov_b32_e32 v204, v144
	v_or_b32_e32 v205, 16, v144
	v_or_b32_e32 v206, 32, v144
	v_or_b32_e32 v207, 48, v144
	v_add_u32_e32 v208, 0x80, v144
	v_add_u32_e32 v209, 0x90, v144
	v_add_u32_e32 v210, 0xa0, v144
	v_add_u32_e32 v211, 0xb0, v144
	v_mad_u32_u24 v204, v204, s86, v148
	v_mad_u32_u24 v205, v205, s86, v148
	v_mad_u32_u24 v206, v206, s86, v148
	v_mad_u32_u24 v207, v207, s86, v148
	v_mad_u32_u24 v208, v208, s86, v148
	v_mad_u32_u24 v209, v209, s86, v148
	v_mad_u32_u24 v210, v210, s86, v148
	v_mad_u32_u24 v211, v211, s86, v148
	s_andn2_b64 vcc, exec, s[6:7]
	s_mov_b32 s98, 0xbfb8aa3b
	v_pk_mul_f32 v[118:119], v[172:173], v[118:119] op_sel_hi:[0,1]
	v_pk_mul_f32 v[120:121], v[172:173], v[120:121] op_sel_hi:[0,1]
	v_pk_mul_f32 v[122:123], v[172:173], v[122:123] op_sel_hi:[0,1]
	v_pk_mul_f32 v[124:125], v[172:173], v[124:125] op_sel_hi:[0,1]
	v_pk_mul_f32 v[126:127], v[172:173], v[126:127] op_sel_hi:[0,1]
	v_pk_mul_f32 v[128:129], v[172:173], v[128:129] op_sel_hi:[0,1]
	v_pk_mul_f32 v[130:131], v[172:173], v[130:131] op_sel_hi:[0,1]
	v_pk_mul_f32 v[132:133], v[172:173], v[132:133] op_sel_hi:[0,1]
	v_pk_mul_f32 v[188:189], v[130:131], s[98:99] op_sel_hi:[1,0]
	v_pk_mul_f32 v[190:191], v[132:133], s[98:99] op_sel_hi:[1,0]
	v_pk_mul_f32 v[192:193], v[126:127], s[98:99] op_sel_hi:[1,0]
	v_pk_mul_f32 v[194:195], v[128:129], s[98:99] op_sel_hi:[1,0]
	v_exp_f32_e32 v188, v188
	v_exp_f32_e32 v189, v189
	v_exp_f32_e32 v190, v190
	v_exp_f32_e32 v191, v191
	v_exp_f32_e32 v192, v192
	v_exp_f32_e32 v193, v193
	v_exp_f32_e32 v194, v194
	v_exp_f32_e32 v195, v195
	v_pk_add_f32 v[188:189], v[188:189], 1.0 op_sel_hi:[1,0]
	v_pk_add_f32 v[190:191], v[190:191], 1.0 op_sel_hi:[1,0]
	v_pk_add_f32 v[192:193], v[192:193], 1.0 op_sel_hi:[1,0]
	v_pk_add_f32 v[194:195], v[194:195], 1.0 op_sel_hi:[1,0]
	v_rcp_f32_e32 v188, v188
	v_rcp_f32_e32 v189, v189
	v_rcp_f32_e32 v190, v190
	v_rcp_f32_e32 v191, v191
	v_rcp_f32_e32 v192, v192
	v_rcp_f32_e32 v193, v193
	v_rcp_f32_e32 v194, v194
	v_rcp_f32_e32 v195, v195
	v_pk_mul_f32 v[188:189], v[130:131], v[188:189]
	v_pk_mul_f32 v[190:191], v[132:133], v[190:191]
	v_pk_mul_f32 v[192:193], v[126:127], v[192:193]
	v_pk_mul_f32 v[194:195], v[128:129], v[194:195]
	v_pk_mul_f32 v[188:189], v[188:189], v[122:123]
	v_pk_mul_f32 v[190:191], v[190:191], v[124:125]
	v_pk_mul_f32 v[192:193], v[192:193], v[118:119]
	v_pk_mul_f32 v[194:195], v[194:195], v[120:121]
	v_cvt_pk_bf16_f32 v196, v188, v189
	v_cvt_pk_bf16_f32 v197, v190, v191
	v_cvt_pk_bf16_f32 v198, v192, v193
	v_cvt_pk_bf16_f32 v199, v194, v195
	global_store_dwordx4 v204, v[196:199], s[76:77] nt
	v_pk_mul_f32 v[102:103], v[174:175], v[102:103] op_sel_hi:[0,1]
	v_pk_mul_f32 v[104:105], v[174:175], v[104:105] op_sel_hi:[0,1]
	v_pk_mul_f32 v[106:107], v[174:175], v[106:107] op_sel_hi:[0,1]
	v_pk_mul_f32 v[108:109], v[174:175], v[108:109] op_sel_hi:[0,1]
	v_pk_mul_f32 v[110:111], v[174:175], v[110:111] op_sel_hi:[0,1]
	v_pk_mul_f32 v[112:113], v[174:175], v[112:113] op_sel_hi:[0,1]
	v_pk_mul_f32 v[114:115], v[174:175], v[114:115] op_sel_hi:[0,1]
	v_pk_mul_f32 v[116:117], v[174:175], v[116:117] op_sel_hi:[0,1]
	v_pk_mul_f32 v[188:189], v[114:115], s[98:99] op_sel_hi:[1,0]
	v_pk_mul_f32 v[190:191], v[116:117], s[98:99] op_sel_hi:[1,0]
	v_pk_mul_f32 v[192:193], v[110:111], s[98:99] op_sel_hi:[1,0]
	v_pk_mul_f32 v[194:195], v[112:113], s[98:99] op_sel_hi:[1,0]
	v_exp_f32_e32 v188, v188
	v_exp_f32_e32 v189, v189
	v_exp_f32_e32 v190, v190
	v_exp_f32_e32 v191, v191
	v_exp_f32_e32 v192, v192
	v_exp_f32_e32 v193, v193
	v_exp_f32_e32 v194, v194
	v_exp_f32_e32 v195, v195
	v_pk_add_f32 v[188:189], v[188:189], 1.0 op_sel_hi:[1,0]
	v_pk_add_f32 v[190:191], v[190:191], 1.0 op_sel_hi:[1,0]
	v_pk_add_f32 v[192:193], v[192:193], 1.0 op_sel_hi:[1,0]
	v_pk_add_f32 v[194:195], v[194:195], 1.0 op_sel_hi:[1,0]
	v_rcp_f32_e32 v188, v188
	v_rcp_f32_e32 v189, v189
	v_rcp_f32_e32 v190, v190
	v_rcp_f32_e32 v191, v191
	v_rcp_f32_e32 v192, v192
	v_rcp_f32_e32 v193, v193
	v_rcp_f32_e32 v194, v194
	v_rcp_f32_e32 v195, v195
	v_pk_mul_f32 v[188:189], v[114:115], v[188:189]
	v_pk_mul_f32 v[190:191], v[116:117], v[190:191]
	v_pk_mul_f32 v[192:193], v[110:111], v[192:193]
	v_pk_mul_f32 v[194:195], v[112:113], v[194:195]
	v_pk_mul_f32 v[188:189], v[188:189], v[106:107]
	v_pk_mul_f32 v[190:191], v[190:191], v[108:109]
	v_pk_mul_f32 v[192:193], v[192:193], v[102:103]
	v_pk_mul_f32 v[194:195], v[194:195], v[104:105]
	v_cvt_pk_bf16_f32 v200, v188, v189
	v_cvt_pk_bf16_f32 v201, v190, v191
	v_cvt_pk_bf16_f32 v202, v192, v193
	v_cvt_pk_bf16_f32 v203, v194, v195
	global_store_dwordx4 v205, v[200:203], s[76:77] nt
	v_pk_mul_f32 v[86:87], v[176:177], v[86:87] op_sel_hi:[0,1]
	v_pk_mul_f32 v[88:89], v[176:177], v[88:89] op_sel_hi:[0,1]
	v_pk_mul_f32 v[90:91], v[176:177], v[90:91] op_sel_hi:[0,1]
	v_pk_mul_f32 v[92:93], v[176:177], v[92:93] op_sel_hi:[0,1]
	v_pk_mul_f32 v[94:95], v[176:177], v[94:95] op_sel_hi:[0,1]
	v_pk_mul_f32 v[96:97], v[176:177], v[96:97] op_sel_hi:[0,1]
; __device__ __forceinline__ unsigned cvt_pk_bf16(float lo, float hi) { unsigned r; asm volatile("v_cvt_pk_bf16_f32 %0, %1, %2" : "=v"(r) : "v"(lo), "v"(hi)); return r; }
; __device__ __forceinline__ float silu_f(float g) { return g * __builtin_amdgcn_rcpf(1.0f + __expf(-g)); }
;     __device__ __forceinline__ void operator()(const f32x4 (&acc)[2][2][4][2], const Unit& u, int wr, int wc, int fr, int fq, const float (&rsv)[8]) const {
;     ...
; #pragma unroll
;         for (int ai = 0; ai < 2; ++ai)
; #pragma unroll
;             for (int m = 0; m < 4; ++m) { bf16_t* rowp = O + (size_t)(row0 + ai * HALF + m * 16) * ldc + col0;
;                 const float rs = __builtin_amdgcn_rsqf(rsv[ai * 4 + m] * (1.0f / 1024.0f) + 1e-6f);
;                 const f32x4 g0 = acc[ai][0][m][0] * rs, g1 = acc[ai][0][m][1] * rs, u0 = acc[ai][1][m][0] * rs, u1 = acc[ai][1][m][1] * rs; u32x4 w;
;                 w.x = cvt_pk_bf16(silu_f(g0[0]) * u0[0], silu_f(g0[1]) * u0[1]); w.y = cvt_pk_bf16(silu_f(g0[2]) * u0[2], silu_f(g0[3]) * u0[3]);
;                 w.z = cvt_pk_bf16(silu_f(g1[0]) * u1[0], silu_f(g1[1]) * u1[1]); w.w = cvt_pk_bf16(silu_f(g1[2]) * u1[2], silu_f(g1[3]) * u1[3]);
;                 __builtin_nontemporal_store(w, (u32x4*)rowp); }
	v_pk_mul_f32 v[98:99], v[176:177], v[98:99] op_sel_hi:[0,1]
	v_pk_mul_f32 v[100:101], v[176:177], v[100:101] op_sel_hi:[0,1]
	v_pk_mul_f32 v[188:189], v[98:99], s[98:99] op_sel_hi:[1,0]
	v_pk_mul_f32 v[190:191], v[100:101], s[98:99] op_sel_hi:[1,0]
	v_pk_mul_f32 v[192:193], v[94:95], s[98:99] op_sel_hi:[1,0]
	v_pk_mul_f32 v[194:195], v[96:97], s[98:99] op_sel_hi:[1,0]
	v_exp_f32_e32 v188, v188
	v_exp_f32_e32 v189, v189
	v_exp_f32_e32 v190, v190
	v_exp_f32_e32 v191, v191
	v_exp_f32_e32 v192, v192
	v_exp_f32_e32 v193, v193
	v_exp_f32_e32 v194, v194
	v_exp_f32_e32 v195, v195
	v_pk_add_f32 v[188:189], v[188:189], 1.0 op_sel_hi:[1,0]
	v_pk_add_f32 v[190:191], v[190:191], 1.0 op_sel_hi:[1,0]
	v_pk_add_f32 v[192:193], v[192:193], 1.0 op_sel_hi:[1,0]
	v_pk_add_f32 v[194:195], v[194:195], 1.0 op_sel_hi:[1,0]
	v_rcp_f32_e32 v188, v188
	v_rcp_f32_e32 v189, v189
	v_rcp_f32_e32 v190, v190
	v_rcp_f32_e32 v191, v191
	v_rcp_f32_e32 v192, v192
	v_rcp_f32_e32 v193, v193
	v_rcp_f32_e32 v194, v194
	v_rcp_f32_e32 v195, v195
	v_pk_mul_f32 v[188:189], v[98:99], v[188:189]
	v_pk_mul_f32 v[190:191], v[100:101], v[190:191]
	v_pk_mul_f32 v[192:193], v[94:95], v[192:193]
	v_pk_mul_f32 v[194:195], v[96:97], v[194:195]
	v_pk_mul_f32 v[188:189], v[188:189], v[90:91]
	v_pk_mul_f32 v[190:191], v[190:191], v[92:93]
	v_pk_mul_f32 v[192:193], v[192:193], v[86:87]
	v_pk_mul_f32 v[194:195], v[194:195], v[88:89]
	v_cvt_pk_bf16_f32 v196, v188, v189
	v_cvt_pk_bf16_f32 v197, v190, v191
	v_cvt_pk_bf16_f32 v198, v192, v193
	v_cvt_pk_bf16_f32 v199, v194, v195
	global_store_dwordx4 v206, v[196:199], s[76:77] nt
	v_pk_mul_f32 v[70:71], v[178:179], v[70:71] op_sel_hi:[0,1]
	v_pk_mul_f32 v[72:73], v[178:179], v[72:73] op_sel_hi:[0,1]
	v_pk_mul_f32 v[74:75], v[178:179], v[74:75] op_sel_hi:[0,1]
	v_pk_mul_f32 v[76:77], v[178:179], v[76:77] op_sel_hi:[0,1]
	v_pk_mul_f32 v[78:79], v[178:179], v[78:79] op_sel_hi:[0,1]
	v_pk_mul_f32 v[80:81], v[178:179], v[80:81] op_sel_hi:[0,1]
	v_pk_mul_f32 v[82:83], v[178:179], v[82:83] op_sel_hi:[0,1]
	v_pk_mul_f32 v[84:85], v[178:179], v[84:85] op_sel_hi:[0,1]
	v_pk_mul_f32 v[188:189], v[82:83], s[98:99] op_sel_hi:[1,0]
	v_pk_mul_f32 v[190:191], v[84:85], s[98:99] op_sel_hi:[1,0]
	v_pk_mul_f32 v[192:193], v[78:79], s[98:99] op_sel_hi:[1,0]
	v_pk_mul_f32 v[194:195], v[80:81], s[98:99] op_sel_hi:[1,0]
	v_exp_f32_e32 v188, v188
	v_exp_f32_e32 v189, v189
	v_exp_f32_e32 v190, v190
	v_exp_f32_e32 v191, v191
	v_exp_f32_e32 v192, v192
	v_exp_f32_e32 v193, v193
	v_exp_f32_e32 v194, v194
	v_exp_f32_e32 v195, v195
	v_pk_add_f32 v[188:189], v[188:189], 1.0 op_sel_hi:[1,0]
	v_pk_add_f32 v[190:191], v[190:191], 1.0 op_sel_hi:[1,0]
	v_pk_add_f32 v[192:193], v[192:193], 1.0 op_sel_hi:[1,0]
	v_pk_add_f32 v[194:195], v[194:195], 1.0 op_sel_hi:[1,0]
	v_rcp_f32_e32 v188, v188
	v_rcp_f32_e32 v189, v189
	v_rcp_f32_e32 v190, v190
	v_rcp_f32_e32 v191, v191
	v_rcp_f32_e32 v192, v192
	v_rcp_f32_e32 v193, v193
	v_rcp_f32_e32 v194, v194
	v_rcp_f32_e32 v195, v195
	v_pk_mul_f32 v[188:189], v[82:83], v[188:189]
	v_pk_mul_f32 v[190:191], v[84:85], v[190:191]
	v_pk_mul_f32 v[192:193], v[78:79], v[192:193]
	v_pk_mul_f32 v[194:195], v[80:81], v[194:195]
	v_pk_mul_f32 v[188:189], v[188:189], v[74:75]
	v_pk_mul_f32 v[190:191], v[190:191], v[76:77]
	v_pk_mul_f32 v[192:193], v[192:193], v[70:71]
	v_pk_mul_f32 v[194:195], v[194:195], v[72:73]
	v_cvt_pk_bf16_f32 v200, v188, v189
	v_cvt_pk_bf16_f32 v201, v190, v191
	v_cvt_pk_bf16_f32 v202, v192, v193
	v_cvt_pk_bf16_f32 v203, v194, v195
	global_store_dwordx4 v207, v[200:203], s[76:77] nt
	v_pk_mul_f32 v[54:55], v[180:181], v[54:55] op_sel_hi:[0,1]
	v_pk_mul_f32 v[56:57], v[180:181], v[56:57] op_sel_hi:[0,1]
	v_pk_mul_f32 v[58:59], v[180:181], v[58:59] op_sel_hi:[0,1]
	v_pk_mul_f32 v[60:61], v[180:181], v[60:61] op_sel_hi:[0,1]
	v_pk_mul_f32 v[62:63], v[180:181], v[62:63] op_sel_hi:[0,1]
	v_pk_mul_f32 v[64:65], v[180:181], v[64:65] op_sel_hi:[0,1]
	v_pk_mul_f32 v[66:67], v[180:181], v[66:67] op_sel_hi:[0,1]
	v_pk_mul_f32 v[68:69], v[180:181], v[68:69] op_sel_hi:[0,1]
	v_pk_mul_f32 v[188:189], v[66:67], s[98:99] op_sel_hi:[1,0]
	v_pk_mul_f32 v[190:191], v[68:69], s[98:99] op_sel_hi:[1,0]
	v_pk_mul_f32 v[192:193], v[62:63], s[98:99] op_sel_hi:[1,0]
	v_pk_mul_f32 v[194:195], v[64:65], s[98:99] op_sel_hi:[1,0]
	v_exp_f32_e32 v188, v188
	v_exp_f32_e32 v189, v189
	v_exp_f32_e32 v190, v190
	v_exp_f32_e32 v191, v191
	v_exp_f32_e32 v192, v192
	v_exp_f32_e32 v193, v193
	v_exp_f32_e32 v194, v194
	v_exp_f32_e32 v195, v195
	v_pk_add_f32 v[188:189], v[188:189], 1.0 op_sel_hi:[1,0]
	v_pk_add_f32 v[190:191], v[190:191], 1.0 op_sel_hi:[1,0]
	v_pk_add_f32 v[192:193], v[192:193], 1.0 op_sel_hi:[1,0]
	v_pk_add_f32 v[194:195], v[194:195], 1.0 op_sel_hi:[1,0]
	v_rcp_f32_e32 v188, v188
	v_rcp_f32_e32 v189, v189
	v_rcp_f32_e32 v190, v190
	v_rcp_f32_e32 v191, v191
	v_rcp_f32_e32 v192, v192
	v_rcp_f32_e32 v193, v193
	v_rcp_f32_e32 v194, v194
	v_rcp_f32_e32 v195, v195
	v_pk_mul_f32 v[188:189], v[66:67], v[188:189]
	v_pk_mul_f32 v[190:191], v[68:69], v[190:191]
	v_pk_mul_f32 v[192:193], v[62:63], v[192:193]
	v_pk_mul_f32 v[194:195], v[64:65], v[194:195]
	v_pk_mul_f32 v[188:189], v[188:189], v[58:59]
	v_pk_mul_f32 v[190:191], v[190:191], v[60:61]
	v_pk_mul_f32 v[192:193], v[192:193], v[54:55]
	v_pk_mul_f32 v[194:195], v[194:195], v[56:57]
	v_cvt_pk_bf16_f32 v196, v188, v189
	v_cvt_pk_bf16_f32 v197, v190, v191
	v_cvt_pk_bf16_f32 v198, v192, v193
	v_cvt_pk_bf16_f32 v199, v194, v195
	global_store_dwordx4 v208, v[196:199], s[76:77] nt
	v_pk_mul_f32 v[38:39], v[182:183], v[38:39] op_sel_hi:[0,1]
	v_pk_mul_f32 v[40:41], v[182:183], v[40:41] op_sel_hi:[0,1]
; __device__ __forceinline__ unsigned cvt_pk_bf16(float lo, float hi) { unsigned r; asm volatile("v_cvt_pk_bf16_f32 %0, %1, %2" : "=v"(r) : "v"(lo), "v"(hi)); return r; }
; __device__ __forceinline__ float silu_f(float g) { return g * __builtin_amdgcn_rcpf(1.0f + __expf(-g)); }
; #define PG8_BAR __builtin_amdgcn_s_barrier()
;     __device__ __forceinline__ void operator()(const f32x4 (&acc)[2][2][4][2], const Unit& u, int wr, int wc, int fr, int fq, const float (&rsv)[8]) const {
;     ...
; #pragma unroll
;         for (int ai = 0; ai < 2; ++ai)
; #pragma unroll
;             for (int m = 0; m < 4; ++m) { bf16_t* rowp = O + (size_t)(row0 + ai * HALF + m * 16) * ldc + col0;
;                 const float rs = __builtin_amdgcn_rsqf(rsv[ai * 4 + m] * (1.0f / 1024.0f) + 1e-6f);
;                 const f32x4 g0 = acc[ai][0][m][0] * rs, g1 = acc[ai][0][m][1] * rs, u0 = acc[ai][1][m][0] * rs, u1 = acc[ai][1][m][1] * rs; u32x4 w;
;                 w.x = cvt_pk_bf16(silu_f(g0[0]) * u0[0], silu_f(g0[1]) * u0[1]); w.y = cvt_pk_bf16(silu_f(g0[2]) * u0[2], silu_f(g0[3]) * u0[3]);
;                 w.z = cvt_pk_bf16(silu_f(g1[0]) * u1[0], silu_f(g1[1]) * u1[1]); w.w = cvt_pk_bf16(silu_f(g1[2]) * u1[2], silu_f(g1[3]) * u1[3]);
;                 __builtin_nontemporal_store(w, (u32x4*)rowp); }
; template <class Epi, class Sched, bool ALIGN_EPI = false, bool SP2 = false>
; __device__ __forceinline__ void gemm_phase(PG8_LAS unsigned char* lds, const Gemm g, const Sched& S, const Epi& E) {
;     ...
;         if (!has_next) break;
; #pragma unroll
;         for (int a = 0; a < 2; ++a)
; #pragma unroll
;             for (int b = 0; b < 2; ++b)
; #pragma unroll
;                 for (int m = 0; m < 4; ++m)
; #pragma unroll
;                     for (int n = 0; n < 2; ++n) acc[a][b][m][n] = (f32x4){0.f, 0.f, 0.f, 0.f};
;         cur = nxt; cA = nA; cB = nB; ++ui;
;         if constexpr (ALIGN_EPI) { if (wr == 1) PG8_BAR; }
	v_pk_mul_f32 v[42:43], v[182:183], v[42:43] op_sel_hi:[0,1]
	v_pk_mul_f32 v[44:45], v[182:183], v[44:45] op_sel_hi:[0,1]
	v_pk_mul_f32 v[46:47], v[182:183], v[46:47] op_sel_hi:[0,1]
	v_pk_mul_f32 v[48:49], v[182:183], v[48:49] op_sel_hi:[0,1]
	v_pk_mul_f32 v[50:51], v[182:183], v[50:51] op_sel_hi:[0,1]
	v_pk_mul_f32 v[52:53], v[182:183], v[52:53] op_sel_hi:[0,1]
	v_pk_mul_f32 v[188:189], v[50:51], s[98:99] op_sel_hi:[1,0]
	v_pk_mul_f32 v[190:191], v[52:53], s[98:99] op_sel_hi:[1,0]
	v_pk_mul_f32 v[192:193], v[46:47], s[98:99] op_sel_hi:[1,0]
	v_pk_mul_f32 v[194:195], v[48:49], s[98:99] op_sel_hi:[1,0]
	v_exp_f32_e32 v188, v188
	v_exp_f32_e32 v189, v189
	v_exp_f32_e32 v190, v190
	v_exp_f32_e32 v191, v191
	v_exp_f32_e32 v192, v192
	v_exp_f32_e32 v193, v193
	v_exp_f32_e32 v194, v194
	v_exp_f32_e32 v195, v195
	v_pk_add_f32 v[188:189], v[188:189], 1.0 op_sel_hi:[1,0]
	v_pk_add_f32 v[190:191], v[190:191], 1.0 op_sel_hi:[1,0]
	v_pk_add_f32 v[192:193], v[192:193], 1.0 op_sel_hi:[1,0]
	v_pk_add_f32 v[194:195], v[194:195], 1.0 op_sel_hi:[1,0]
	v_rcp_f32_e32 v188, v188
	v_rcp_f32_e32 v189, v189
	v_rcp_f32_e32 v190, v190
	v_rcp_f32_e32 v191, v191
	v_rcp_f32_e32 v192, v192
	v_rcp_f32_e32 v193, v193
	v_rcp_f32_e32 v194, v194
	v_rcp_f32_e32 v195, v195
	v_pk_mul_f32 v[188:189], v[50:51], v[188:189]
	v_pk_mul_f32 v[190:191], v[52:53], v[190:191]
	v_pk_mul_f32 v[192:193], v[46:47], v[192:193]
	v_pk_mul_f32 v[194:195], v[48:49], v[194:195]
	v_pk_mul_f32 v[188:189], v[188:189], v[42:43]
	v_pk_mul_f32 v[190:191], v[190:191], v[44:45]
	v_pk_mul_f32 v[192:193], v[192:193], v[38:39]
	v_pk_mul_f32 v[194:195], v[194:195], v[40:41]
	v_cvt_pk_bf16_f32 v200, v188, v189
	v_cvt_pk_bf16_f32 v201, v190, v191
	v_cvt_pk_bf16_f32 v202, v192, v193
	v_cvt_pk_bf16_f32 v203, v194, v195
	global_store_dwordx4 v209, v[200:203], s[76:77] nt
	v_pk_mul_f32 v[22:23], v[184:185], v[22:23] op_sel_hi:[0,1]
	v_pk_mul_f32 v[24:25], v[184:185], v[24:25] op_sel_hi:[0,1]
	v_pk_mul_f32 v[26:27], v[184:185], v[26:27] op_sel_hi:[0,1]
	v_pk_mul_f32 v[28:29], v[184:185], v[28:29] op_sel_hi:[0,1]
	v_pk_mul_f32 v[30:31], v[184:185], v[30:31] op_sel_hi:[0,1]
	v_pk_mul_f32 v[32:33], v[184:185], v[32:33] op_sel_hi:[0,1]
	v_pk_mul_f32 v[34:35], v[184:185], v[34:35] op_sel_hi:[0,1]
	v_pk_mul_f32 v[36:37], v[184:185], v[36:37] op_sel_hi:[0,1]
	v_pk_mul_f32 v[188:189], v[34:35], s[98:99] op_sel_hi:[1,0]
	v_pk_mul_f32 v[190:191], v[36:37], s[98:99] op_sel_hi:[1,0]
	v_pk_mul_f32 v[192:193], v[30:31], s[98:99] op_sel_hi:[1,0]
	v_pk_mul_f32 v[194:195], v[32:33], s[98:99] op_sel_hi:[1,0]
	v_exp_f32_e32 v188, v188
	v_exp_f32_e32 v189, v189
	v_exp_f32_e32 v190, v190
	v_exp_f32_e32 v191, v191
	v_exp_f32_e32 v192, v192
	v_exp_f32_e32 v193, v193
	v_exp_f32_e32 v194, v194
	v_exp_f32_e32 v195, v195
	v_pk_add_f32 v[188:189], v[188:189], 1.0 op_sel_hi:[1,0]
	v_pk_add_f32 v[190:191], v[190:191], 1.0 op_sel_hi:[1,0]
	v_pk_add_f32 v[192:193], v[192:193], 1.0 op_sel_hi:[1,0]
	v_pk_add_f32 v[194:195], v[194:195], 1.0 op_sel_hi:[1,0]
	v_rcp_f32_e32 v188, v188
	v_rcp_f32_e32 v189, v189
	v_rcp_f32_e32 v190, v190
	v_rcp_f32_e32 v191, v191
	v_rcp_f32_e32 v192, v192
	v_rcp_f32_e32 v193, v193
	v_rcp_f32_e32 v194, v194
	v_rcp_f32_e32 v195, v195
	v_pk_mul_f32 v[188:189], v[34:35], v[188:189]
	v_pk_mul_f32 v[190:191], v[36:37], v[190:191]
	v_pk_mul_f32 v[192:193], v[30:31], v[192:193]
	v_pk_mul_f32 v[194:195], v[32:33], v[194:195]
	v_pk_mul_f32 v[188:189], v[188:189], v[26:27]
	v_pk_mul_f32 v[190:191], v[190:191], v[28:29]
	v_pk_mul_f32 v[192:193], v[192:193], v[22:23]
	v_pk_mul_f32 v[194:195], v[194:195], v[24:25]
	v_cvt_pk_bf16_f32 v196, v188, v189
	v_cvt_pk_bf16_f32 v197, v190, v191
	v_cvt_pk_bf16_f32 v198, v192, v193
	v_cvt_pk_bf16_f32 v199, v194, v195
	global_store_dwordx4 v210, v[196:199], s[76:77] nt
	v_pk_mul_f32 v[6:7], v[186:187], v[6:7] op_sel_hi:[0,1]
	v_pk_mul_f32 v[8:9], v[186:187], v[8:9] op_sel_hi:[0,1]
	v_pk_mul_f32 v[10:11], v[186:187], v[10:11] op_sel_hi:[0,1]
	v_pk_mul_f32 v[12:13], v[186:187], v[12:13] op_sel_hi:[0,1]
	v_pk_mul_f32 v[14:15], v[186:187], v[14:15] op_sel_hi:[0,1]
	v_pk_mul_f32 v[16:17], v[186:187], v[16:17] op_sel_hi:[0,1]
	v_pk_mul_f32 v[18:19], v[186:187], v[18:19] op_sel_hi:[0,1]
	v_pk_mul_f32 v[20:21], v[186:187], v[20:21] op_sel_hi:[0,1]
	v_pk_mul_f32 v[188:189], v[18:19], s[98:99] op_sel_hi:[1,0]
	v_pk_mul_f32 v[190:191], v[20:21], s[98:99] op_sel_hi:[1,0]
	v_pk_mul_f32 v[192:193], v[14:15], s[98:99] op_sel_hi:[1,0]
	v_pk_mul_f32 v[194:195], v[16:17], s[98:99] op_sel_hi:[1,0]
	v_exp_f32_e32 v188, v188
	v_exp_f32_e32 v189, v189
	v_exp_f32_e32 v190, v190
	v_exp_f32_e32 v191, v191
	v_exp_f32_e32 v192, v192
	v_exp_f32_e32 v193, v193
	v_exp_f32_e32 v194, v194
	v_exp_f32_e32 v195, v195
	v_pk_add_f32 v[188:189], v[188:189], 1.0 op_sel_hi:[1,0]
	v_pk_add_f32 v[190:191], v[190:191], 1.0 op_sel_hi:[1,0]
	v_pk_add_f32 v[192:193], v[192:193], 1.0 op_sel_hi:[1,0]
	v_pk_add_f32 v[194:195], v[194:195], 1.0 op_sel_hi:[1,0]
	v_rcp_f32_e32 v188, v188
	v_rcp_f32_e32 v189, v189
	v_rcp_f32_e32 v190, v190
	v_rcp_f32_e32 v191, v191
	v_rcp_f32_e32 v192, v192
	v_rcp_f32_e32 v193, v193
	v_rcp_f32_e32 v194, v194
	v_rcp_f32_e32 v195, v195
	v_pk_mul_f32 v[188:189], v[18:19], v[188:189]
	v_pk_mul_f32 v[190:191], v[20:21], v[190:191]
	v_pk_mul_f32 v[192:193], v[14:15], v[192:193]
	v_pk_mul_f32 v[194:195], v[16:17], v[194:195]
	v_pk_mul_f32 v[188:189], v[188:189], v[10:11]
	v_pk_mul_f32 v[190:191], v[190:191], v[12:13]
	v_pk_mul_f32 v[192:193], v[192:193], v[6:7]
	v_pk_mul_f32 v[194:195], v[194:195], v[8:9]
	v_cvt_pk_bf16_f32 v200, v188, v189
	v_cvt_pk_bf16_f32 v201, v190, v191
	v_cvt_pk_bf16_f32 v202, v192, v193
	v_cvt_pk_bf16_f32 v203, v194, v195
	global_store_dwordx4 v211, v[200:203], s[76:77] nt
	s_mov_b64 s[4:5], -1
	s_branch .Lepisw_pad_end
	s_nop 0
	s_nop 0
	s_nop 0
	s_nop 0
	s_nop 0
	s_nop 0
	s_nop 0
	s_nop 0
	s_nop 0
	s_nop 0
	s_nop 0
	s_nop 0
	s_nop 0
	s_nop 0
	s_nop 0
	s_nop 0
	s_nop 0
	s_nop 0
	s_nop 0
	s_nop 0
	s_nop 0
	s_nop 0
	s_nop 0
	s_nop 0
	s_nop 0
	s_nop 0
	s_nop 0
	s_nop 0
	s_nop 0
	s_nop 0
	s_nop 0
	s_nop 0
	s_nop 0
	s_nop 0
	s_nop 0
	s_nop 0
	s_nop 0
	s_nop 0
	s_nop 0
	s_nop 0
	s_nop 0
	s_nop 0
	s_nop 0
	s_nop 0
	s_nop 0
	s_nop 0
	s_nop 0
	s_nop 0
	s_nop 0
	s_nop 0
	s_nop 0
	s_nop 0
	s_nop 0
	s_nop 0
	s_nop 0
	s_nop 0
	s_nop 0
	s_nop 0
	s_nop 0
	s_nop 0
	s_nop 0
	s_nop 0
	s_nop 0
	s_nop 0
	s_nop 0
	s_nop 0
	s_nop 0
	s_nop 0
	s_nop 0
	s_nop 0
	s_nop 0
	s_nop 0
	s_nop 0
	s_nop 0
	s_nop 0
	s_nop 0
	s_nop 0
	s_nop 0
	s_nop 0
	s_nop 0
	s_nop 0
	s_nop 0
	s_nop 0
	s_nop 0
	s_nop 0
	s_nop 0
	s_nop 0
	s_nop 0
	s_nop 0
	s_nop 0
	s_nop 0
	s_nop 0
	s_nop 0
	s_nop 0
	s_nop 0
	s_nop 0
	s_nop 0
	s_nop 0
	s_nop 0
	s_nop 0
	s_nop 0
	s_nop 0
	s_nop 0
	s_nop 0
	s_nop 0
	s_nop 0
	s_nop 0
	s_nop 0
	s_nop 0
	s_nop 0
	s_nop 0
	s_nop 0
	s_nop 0
	s_nop 0
	s_nop 0
	s_nop 0
	s_nop 0
.Lepisw_pad_end:
	s_cbranch_vccnz .LBB0_1099
	s_andn2_b64 vcc, exec, s[0:1]
	s_cbranch_vccnz .LBB0_1098
	s_barrier
	s_branch .LBB0_1098
